# split-K slab sums of the last row panel streamed slab by slab for 4 row pieces at a time (double-buffered, counted vmcnt, SGPR base + lane offset) instead of 8 serial pieces
# speedup vs baseline: 1.0629x; 1.0087x over previous
.LBB0_951:
	v_add_u32_e32 v0, 0xffffe000, v38
	s_movk_i32 s1, 0x1fff
	v_lshlrev_b64 v[64:65], 13, v[0:1]
	v_cmp_lt_i32_e64 s[42:43], s1, v38
	v_lshl_add_u64 v[22:23], v[40:41], 0, v[64:65]
	s_and_saveexec_b64 s[18:19], s[42:43]
	s_cbranch_execz .LBB0_953
	v_readfirstlane_b32 s98, v22
	v_readfirstlane_b32 s99, v23
	s_nop 1
	v_subrev_u32_e32 v174, s98, v22
	s_add_u32 s100, s98, 0x1000
	s_addc_u32 s101, s99, 0

.LBB0_955:
.LBB0_956:
	s_or_b64 exec, exec, s[18:19]
	s_and_b64 vcc, exec, s[44:45]
	s_cbranch_vccnz .LBB0_974
	global_load_dwordx4 v[14:17], v[58:59], off offset:-2048 nt
	s_and_saveexec_b64 s[18:19], s[42:43]
	s_cbranch_execz .LBB0_959
.LBB0_958:
.LBB0_959:
	s_or_b64 exec, exec, s[18:19]
	s_and_b64 vcc, exec, s[44:45]
	s_cbranch_vccnz .LBB0_975
	global_load_dwordx4 v[18:21], v[58:59], off offset:-1024 nt
	s_and_saveexec_b64 s[18:19], s[42:43]
	s_cbranch_execz .LBB0_962
.LBB0_961:
.LBB0_962:
	s_or_b64 exec, exec, s[18:19]
	s_and_b64 vcc, exec, s[44:45]
	s_cbranch_vccnz .LBB0_976
	global_load_dwordx4 v[22:25], v[58:59], off nt
	s_and_saveexec_b64 s[18:19], s[42:43]
	s_cbranch_execz .LBB0_965
.LBB0_964:
	v_lshl_add_u64 v[74:75], v[42:43], 0, v[64:65]
.LBB0_965:
	s_or_b64 exec, exec, s[18:19]
	s_and_b64 vcc, exec, s[44:45]
	s_cbranch_vccnz .LBB0_977
	global_load_dwordx4 v[26:29], v[58:59], off offset:1024 nt
	s_and_saveexec_b64 s[18:19], s[42:43]
	s_cbranch_execz .LBB0_968
.LBB0_967:
	v_lshl_add_u64 v[78:79], v[44:45], 0, v[64:65]
.LBB0_968:
	s_or_b64 exec, exec, s[18:19]
	s_and_b64 vcc, exec, s[44:45]
	s_cbranch_vccnz .LBB0_978
	global_load_dwordx4 v[30:33], v[58:59], off offset:2048 nt
	s_and_saveexec_b64 s[18:19], s[42:43]
	s_cbranch_execz .LBB0_971
.LBB0_970:
	v_lshl_add_u64 v[82:83], v[46:47], 0, v[64:65]
.LBB0_971:
	s_or_b64 exec, exec, s[18:19]
	s_and_b64 vcc, exec, s[44:45]
	s_cbranch_vccnz .LBB0_979
	global_load_dwordx4 v[34:37], v[58:59], off offset:3072 nt
	s_and_saveexec_b64 s[18:19], s[42:43]
	s_cbranch_execz .LBB0_945
	s_branch .LBB0_980

.LBB0_980:
	v_lshl_add_u64 v[84:85], v[48:49], 0, v[64:65]
	s_waitcnt vmcnt(0)
	v_mov_b32_e32 v214, v6
	v_mov_b32_e32 v215, v7
	v_mov_b32_e32 v216, v8
	v_mov_b32_e32 v217, v9
	v_mov_b32_e32 v218, v10
	v_mov_b32_e32 v219, v11
	v_mov_b32_e32 v220, v12
	v_mov_b32_e32 v221, v13
	v_mov_b32_e32 v222, v14
	v_mov_b32_e32 v223, v15
	v_mov_b32_e32 v224, v16
	v_mov_b32_e32 v225, v17
	v_mov_b32_e32 v226, v18
	v_mov_b32_e32 v227, v19
	v_mov_b32_e32 v228, v20
	v_mov_b32_e32 v229, v21
	v_mov_b32_e32 v230, v22
	v_mov_b32_e32 v231, v23
	v_mov_b32_e32 v232, v24
	v_mov_b32_e32 v233, v25
	v_mov_b32_e32 v234, v26
	v_mov_b32_e32 v235, v27
	v_mov_b32_e32 v236, v28
	v_mov_b32_e32 v237, v29
	v_mov_b32_e32 v238, v30
	v_mov_b32_e32 v239, v31
	v_mov_b32_e32 v240, v32
	v_mov_b32_e32 v241, v33
	v_mov_b32_e32 v242, v34
	v_mov_b32_e32 v243, v35
	v_mov_b32_e32 v244, v36
	v_mov_b32_e32 v245, v37
	s_nop 3
	global_load_dwordx4 v[138:141], v174, s[98:99]
	global_load_dwordx4 v[142:145], v174, s[98:99] offset:1024
	global_load_dwordx4 v[146:149], v174, s[98:99] offset:2048
	global_load_dwordx4 v[150:153], v174, s[98:99] offset:3072
	s_add_u32 s98, s98, 0x200000
	s_addc_u32 s99, s99, 0
	global_load_dwordx4 v[154:157], v174, s[98:99]
	global_load_dwordx4 v[158:161], v174, s[98:99] offset:1024
	global_load_dwordx4 v[162:165], v174, s[98:99] offset:2048
	global_load_dwordx4 v[170:173], v174, s[98:99] offset:3072
	s_waitcnt vmcnt(4)
	v_pk_add_f32 v[214:215], v[214:215], v[138:139]
	v_pk_add_f32 v[216:217], v[216:217], v[140:141]
	v_pk_add_f32 v[218:219], v[218:219], v[142:143]
	v_pk_add_f32 v[220:221], v[220:221], v[144:145]
	v_pk_add_f32 v[222:223], v[222:223], v[146:147]
	v_pk_add_f32 v[224:225], v[224:225], v[148:149]
	v_pk_add_f32 v[226:227], v[226:227], v[150:151]
	v_pk_add_f32 v[228:229], v[228:229], v[152:153]
	s_add_u32 s98, s98, 0x200000
	s_addc_u32 s99, s99, 0
	global_load_dwordx4 v[138:141], v174, s[98:99]
	global_load_dwordx4 v[142:145], v174, s[98:99] offset:1024
	global_load_dwordx4 v[146:149], v174, s[98:99] offset:2048
	global_load_dwordx4 v[150:153], v174, s[98:99] offset:3072
	s_waitcnt vmcnt(4)
	v_pk_add_f32 v[214:215], v[214:215], v[154:155]
	v_pk_add_f32 v[216:217], v[216:217], v[156:157]
	v_pk_add_f32 v[218:219], v[218:219], v[158:159]
	v_pk_add_f32 v[220:221], v[220:221], v[160:161]
	v_pk_add_f32 v[222:223], v[222:223], v[162:163]
	v_pk_add_f32 v[224:225], v[224:225], v[164:165]
	v_pk_add_f32 v[226:227], v[226:227], v[170:171]
	v_pk_add_f32 v[228:229], v[228:229], v[172:173]
	s_add_u32 s98, s98, 0x200000
	s_addc_u32 s99, s99, 0
	global_load_dwordx4 v[154:157], v174, s[98:99]
	global_load_dwordx4 v[158:161], v174, s[98:99] offset:1024
	global_load_dwordx4 v[162:165], v174, s[98:99] offset:2048
	global_load_dwordx4 v[170:173], v174, s[98:99] offset:3072
	s_waitcnt vmcnt(4)
	v_pk_add_f32 v[214:215], v[214:215], v[138:139]
	v_pk_add_f32 v[216:217], v[216:217], v[140:141]
	v_pk_add_f32 v[218:219], v[218:219], v[142:143]
	v_pk_add_f32 v[220:221], v[220:221], v[144:145]
	v_pk_add_f32 v[222:223], v[222:223], v[146:147]
	v_pk_add_f32 v[224:225], v[224:225], v[148:149]
	v_pk_add_f32 v[226:227], v[226:227], v[150:151]
	v_pk_add_f32 v[228:229], v[228:229], v[152:153]
	s_add_u32 s98, s98, 0x200000
	s_addc_u32 s99, s99, 0
	global_load_dwordx4 v[138:141], v174, s[98:99]
	global_load_dwordx4 v[142:145], v174, s[98:99] offset:1024
	global_load_dwordx4 v[146:149], v174, s[98:99] offset:2048
	global_load_dwordx4 v[150:153], v174, s[98:99] offset:3072
	s_waitcnt vmcnt(4)
	v_pk_add_f32 v[214:215], v[214:215], v[154:155]
	v_pk_add_f32 v[216:217], v[216:217], v[156:157]
	v_pk_add_f32 v[218:219], v[218:219], v[158:159]
	v_pk_add_f32 v[220:221], v[220:221], v[160:161]
	v_pk_add_f32 v[222:223], v[222:223], v[162:163]
	v_pk_add_f32 v[224:225], v[224:225], v[164:165]
	v_pk_add_f32 v[226:227], v[226:227], v[170:171]
	v_pk_add_f32 v[228:229], v[228:229], v[172:173]
	s_add_u32 s98, s98, 0x200000
	s_addc_u32 s99, s99, 0
	global_load_dwordx4 v[154:157], v174, s[98:99]
	global_load_dwordx4 v[158:161], v174, s[98:99] offset:1024
	global_load_dwordx4 v[162:165], v174, s[98:99] offset:2048
	global_load_dwordx4 v[170:173], v174, s[98:99] offset:3072
	s_waitcnt vmcnt(4)
	v_pk_add_f32 v[214:215], v[214:215], v[138:139]
	v_pk_add_f32 v[216:217], v[216:217], v[140:141]
	v_pk_add_f32 v[218:219], v[218:219], v[142:143]
	v_pk_add_f32 v[220:221], v[220:221], v[144:145]
	v_pk_add_f32 v[222:223], v[222:223], v[146:147]
	v_pk_add_f32 v[224:225], v[224:225], v[148:149]
	v_pk_add_f32 v[226:227], v[226:227], v[150:151]
	v_pk_add_f32 v[228:229], v[228:229], v[152:153]
	s_add_u32 s98, s98, 0x200000
	s_addc_u32 s99, s99, 0
	global_load_dwordx4 v[138:141], v174, s[98:99]
	global_load_dwordx4 v[142:145], v174, s[98:99] offset:1024
	global_load_dwordx4 v[146:149], v174, s[98:99] offset:2048
	global_load_dwordx4 v[150:153], v174, s[98:99] offset:3072
	s_waitcnt vmcnt(4)
	v_pk_add_f32 v[214:215], v[214:215], v[154:155]
	v_pk_add_f32 v[216:217], v[216:217], v[156:157]
	v_pk_add_f32 v[218:219], v[218:219], v[158:159]
	v_pk_add_f32 v[220:221], v[220:221], v[160:161]
	v_pk_add_f32 v[222:223], v[222:223], v[162:163]
	v_pk_add_f32 v[224:225], v[224:225], v[164:165]
	v_pk_add_f32 v[226:227], v[226:227], v[170:171]
	v_pk_add_f32 v[228:229], v[228:229], v[172:173]
	s_add_u32 s98, s98, 0x200000
	s_addc_u32 s99, s99, 0
	global_load_dwordx4 v[154:157], v174, s[98:99]
	global_load_dwordx4 v[158:161], v174, s[98:99] offset:1024
	global_load_dwordx4 v[162:165], v174, s[98:99] offset:2048
	global_load_dwordx4 v[170:173], v174, s[98:99] offset:3072
	s_waitcnt vmcnt(4)
	v_pk_add_f32 v[214:215], v[214:215], v[138:139]
	v_pk_add_f32 v[216:217], v[216:217], v[140:141]
	v_pk_add_f32 v[218:219], v[218:219], v[142:143]
	v_pk_add_f32 v[220:221], v[220:221], v[144:145]
	v_pk_add_f32 v[222:223], v[222:223], v[146:147]
	v_pk_add_f32 v[224:225], v[224:225], v[148:149]
	v_pk_add_f32 v[226:227], v[226:227], v[150:151]
	v_pk_add_f32 v[228:229], v[228:229], v[152:153]
	s_waitcnt vmcnt(0)
	v_pk_add_f32 v[214:215], v[214:215], v[154:155]
	v_pk_add_f32 v[216:217], v[216:217], v[156:157]
	v_pk_add_f32 v[218:219], v[218:219], v[158:159]
	v_pk_add_f32 v[220:221], v[220:221], v[160:161]
	v_pk_add_f32 v[222:223], v[222:223], v[162:163]
	v_pk_add_f32 v[224:225], v[224:225], v[164:165]
	v_pk_add_f32 v[226:227], v[226:227], v[170:171]
	v_pk_add_f32 v[228:229], v[228:229], v[172:173]
	global_load_dwordx4 v[138:141], v174, s[100:101]
	global_load_dwordx4 v[142:145], v174, s[100:101] offset:1024
	global_load_dwordx4 v[146:149], v174, s[100:101] offset:2048
	global_load_dwordx4 v[150:153], v174, s[100:101] offset:3072
	s_add_u32 s100, s100, 0x200000
	s_addc_u32 s101, s101, 0
	global_load_dwordx4 v[154:157], v174, s[100:101]
	global_load_dwordx4 v[158:161], v174, s[100:101] offset:1024
	global_load_dwordx4 v[162:165], v174, s[100:101] offset:2048
	global_load_dwordx4 v[170:173], v174, s[100:101] offset:3072
	s_waitcnt vmcnt(4)
	v_pk_add_f32 v[230:231], v[230:231], v[138:139]
	v_pk_add_f32 v[232:233], v[232:233], v[140:141]
	v_pk_add_f32 v[234:235], v[234:235], v[142:143]
	v_pk_add_f32 v[236:237], v[236:237], v[144:145]
	v_pk_add_f32 v[238:239], v[238:239], v[146:147]
	v_pk_add_f32 v[240:241], v[240:241], v[148:149]
	v_pk_add_f32 v[242:243], v[242:243], v[150:151]
	v_pk_add_f32 v[244:245], v[244:245], v[152:153]
	s_add_u32 s100, s100, 0x200000
	s_addc_u32 s101, s101, 0
	global_load_dwordx4 v[138:141], v174, s[100:101]
	global_load_dwordx4 v[142:145], v174, s[100:101] offset:1024
	global_load_dwordx4 v[146:149], v174, s[100:101] offset:2048
	global_load_dwordx4 v[150:153], v174, s[100:101] offset:3072
	s_waitcnt vmcnt(4)
	v_pk_add_f32 v[230:231], v[230:231], v[154:155]
	v_pk_add_f32 v[232:233], v[232:233], v[156:157]
	v_pk_add_f32 v[234:235], v[234:235], v[158:159]
	v_pk_add_f32 v[236:237], v[236:237], v[160:161]
	v_pk_add_f32 v[238:239], v[238:239], v[162:163]
	v_pk_add_f32 v[240:241], v[240:241], v[164:165]
	v_pk_add_f32 v[242:243], v[242:243], v[170:171]
	v_pk_add_f32 v[244:245], v[244:245], v[172:173]
	s_add_u32 s100, s100, 0x200000
	s_addc_u32 s101, s101, 0
	global_load_dwordx4 v[154:157], v174, s[100:101]
	global_load_dwordx4 v[158:161], v174, s[100:101] offset:1024
	global_load_dwordx4 v[162:165], v174, s[100:101] offset:2048
	global_load_dwordx4 v[170:173], v174, s[100:101] offset:3072
	s_waitcnt vmcnt(4)
	v_pk_add_f32 v[230:231], v[230:231], v[138:139]
	v_pk_add_f32 v[232:233], v[232:233], v[140:141]
	v_pk_add_f32 v[234:235], v[234:235], v[142:143]
	v_pk_add_f32 v[236:237], v[236:237], v[144:145]
	v_pk_add_f32 v[238:239], v[238:239], v[146:147]
	v_pk_add_f32 v[240:241], v[240:241], v[148:149]
	v_pk_add_f32 v[242:243], v[242:243], v[150:151]
	v_pk_add_f32 v[244:245], v[244:245], v[152:153]
	s_add_u32 s100, s100, 0x200000
	s_addc_u32 s101, s101, 0
	global_load_dwordx4 v[138:141], v174, s[100:101]
	global_load_dwordx4 v[142:145], v174, s[100:101] offset:1024
	global_load_dwordx4 v[146:149], v174, s[100:101] offset:2048
	global_load_dwordx4 v[150:153], v174, s[100:101] offset:3072
	s_waitcnt vmcnt(4)
	v_pk_add_f32 v[230:231], v[230:231], v[154:155]
	v_pk_add_f32 v[232:233], v[232:233], v[156:157]
	v_pk_add_f32 v[234:235], v[234:235], v[158:159]
	v_pk_add_f32 v[236:237], v[236:237], v[160:161]
	v_pk_add_f32 v[238:239], v[238:239], v[162:163]
	v_pk_add_f32 v[240:241], v[240:241], v[164:165]
	v_pk_add_f32 v[242:243], v[242:243], v[170:171]
	v_pk_add_f32 v[244:245], v[244:245], v[172:173]
	s_add_u32 s100, s100, 0x200000
	s_addc_u32 s101, s101, 0
	global_load_dwordx4 v[154:157], v174, s[100:101]
	global_load_dwordx4 v[158:161], v174, s[100:101] offset:1024
	global_load_dwordx4 v[162:165], v174, s[100:101] offset:2048
	global_load_dwordx4 v[170:173], v174, s[100:101] offset:3072
	s_waitcnt vmcnt(4)
	v_pk_add_f32 v[230:231], v[230:231], v[138:139]
	v_pk_add_f32 v[232:233], v[232:233], v[140:141]
	v_pk_add_f32 v[234:235], v[234:235], v[142:143]
	v_pk_add_f32 v[236:237], v[236:237], v[144:145]
	v_pk_add_f32 v[238:239], v[238:239], v[146:147]
	v_pk_add_f32 v[240:241], v[240:241], v[148:149]
	v_pk_add_f32 v[242:243], v[242:243], v[150:151]
	v_pk_add_f32 v[244:245], v[244:245], v[152:153]
	s_add_u32 s100, s100, 0x200000
	s_addc_u32 s101, s101, 0
	global_load_dwordx4 v[138:141], v174, s[100:101]
	global_load_dwordx4 v[142:145], v174, s[100:101] offset:1024
	global_load_dwordx4 v[146:149], v174, s[100:101] offset:2048
	global_load_dwordx4 v[150:153], v174, s[100:101] offset:3072
	s_waitcnt vmcnt(4)
	v_pk_add_f32 v[230:231], v[230:231], v[154:155]
	v_pk_add_f32 v[232:233], v[232:233], v[156:157]
	v_pk_add_f32 v[234:235], v[234:235], v[158:159]
	v_pk_add_f32 v[236:237], v[236:237], v[160:161]
	v_pk_add_f32 v[238:239], v[238:239], v[162:163]
	v_pk_add_f32 v[240:241], v[240:241], v[164:165]
	v_pk_add_f32 v[242:243], v[242:243], v[170:171]
	v_pk_add_f32 v[244:245], v[244:245], v[172:173]
	s_add_u32 s100, s100, 0x200000
	s_addc_u32 s101, s101, 0
	global_load_dwordx4 v[154:157], v174, s[100:101]
	global_load_dwordx4 v[158:161], v174, s[100:101] offset:1024
	global_load_dwordx4 v[162:165], v174, s[100:101] offset:2048
	global_load_dwordx4 v[170:173], v174, s[100:101] offset:3072
	s_waitcnt vmcnt(4)
	v_pk_add_f32 v[230:231], v[230:231], v[138:139]
	v_pk_add_f32 v[232:233], v[232:233], v[140:141]
	v_pk_add_f32 v[234:235], v[234:235], v[142:143]
	v_pk_add_f32 v[236:237], v[236:237], v[144:145]
	v_pk_add_f32 v[238:239], v[238:239], v[146:147]
	v_pk_add_f32 v[240:241], v[240:241], v[148:149]
	v_pk_add_f32 v[242:243], v[242:243], v[150:151]
	v_pk_add_f32 v[244:245], v[244:245], v[152:153]
	s_waitcnt vmcnt(0)
	v_pk_add_f32 v[230:231], v[230:231], v[154:155]
	v_pk_add_f32 v[232:233], v[232:233], v[156:157]
	v_pk_add_f32 v[234:235], v[234:235], v[158:159]
	v_pk_add_f32 v[236:237], v[236:237], v[160:161]
	v_pk_add_f32 v[238:239], v[238:239], v[162:163]
	v_pk_add_f32 v[240:241], v[240:241], v[164:165]
	v_pk_add_f32 v[242:243], v[242:243], v[170:171]
	v_pk_add_f32 v[244:245], v[244:245], v[172:173]
	v_mov_b32_e32 v6, v214
	v_mov_b32_e32 v7, v215
	v_mov_b32_e32 v8, v216
	v_mov_b32_e32 v9, v217
	v_mov_b32_e32 v10, v218
	v_mov_b32_e32 v11, v219
	v_mov_b32_e32 v12, v220
	v_mov_b32_e32 v13, v221
	v_mov_b32_e32 v14, v222
	v_mov_b32_e32 v15, v223
	v_mov_b32_e32 v16, v224
	v_mov_b32_e32 v17, v225
	v_mov_b32_e32 v18, v226
	v_mov_b32_e32 v19, v227
	v_mov_b32_e32 v20, v228
	v_mov_b32_e32 v21, v229
	v_mov_b32_e32 v22, v230
	v_mov_b32_e32 v23, v231
	v_mov_b32_e32 v24, v232
	v_mov_b32_e32 v25, v233
	v_mov_b32_e32 v26, v234
	v_mov_b32_e32 v27, v235
	v_mov_b32_e32 v28, v236
	v_mov_b32_e32 v29, v237
	v_mov_b32_e32 v30, v238
	v_mov_b32_e32 v31, v239
	v_mov_b32_e32 v32, v240
	v_mov_b32_e32 v33, v241
	v_mov_b32_e32 v34, v242
	v_mov_b32_e32 v35, v243
	v_mov_b32_e32 v36, v244
	v_mov_b32_e32 v37, v245
	s_branch .LBB0_945

.LBB0_994:
	s_or_b64 exec, exec, s[18:19]
	v_add_u32_e32 v10, 0xffffe000, v38
	v_mov_b32_e32 v11, v1
	s_movk_i32 s1, 0x1fff
	v_lshlrev_b64 v[58:59], 13, v[10:11]
	v_cmp_lt_i32_e64 s[42:43], s1, v38
	v_lshl_add_u64 v[22:23], v[40:41], 0, v[58:59]
	s_and_saveexec_b64 s[18:19], s[42:43]
	s_cbranch_execz .LBB0_996
	v_readfirstlane_b32 s98, v22
	v_readfirstlane_b32 s99, v23
	s_nop 1
	v_subrev_u32_e32 v174, s98, v22
	s_add_u32 s100, s98, 0x1000
	s_addc_u32 s101, s99, 0

.LBB0_998:
	s_or_b64 exec, exec, s[18:19]
	s_and_saveexec_b64 s[18:19], s[42:43]
	s_cbranch_execz .LBB0_1000
.LBB0_1000:
	s_or_b64 exec, exec, s[18:19]
	v_mov_b32_e32 v14, v1
	v_mov_b32_e32 v15, v1
	v_mov_b64_e32 v[16:17], v[14:15]
	s_and_saveexec_b64 s[18:19], s[44:45]
	s_cbranch_execz .LBB0_1002
	global_load_dwordx4 v[14:17], v[56:57], off offset:2048 nt
.LBB0_1002:
	s_or_b64 exec, exec, s[18:19]
	s_and_saveexec_b64 s[18:19], s[42:43]
	s_cbranch_execz .LBB0_1004
.LBB0_1004:
	s_or_b64 exec, exec, s[18:19]
	v_mov_b32_e32 v18, v1
	v_mov_b32_e32 v19, v1
	v_mov_b64_e32 v[20:21], v[18:19]
	s_and_saveexec_b64 s[18:19], s[44:45]
	s_cbranch_execz .LBB0_1006
	global_load_dwordx4 v[18:21], v[56:57], off offset:3072 nt
.LBB0_1006:
	s_or_b64 exec, exec, s[18:19]
	s_and_saveexec_b64 s[18:19], s[42:43]
	s_cbranch_execz .LBB0_1008
.LBB0_1008:
	s_or_b64 exec, exec, s[18:19]
	v_mov_b32_e32 v22, v1
	v_mov_b32_e32 v23, v1
	v_mov_b64_e32 v[24:25], v[22:23]
	s_and_saveexec_b64 s[18:19], s[44:45]
	s_cbranch_execz .LBB0_1010
	v_add_co_u32_e32 v22, vcc, 0x1000, v56
	s_nop 1
	v_addc_co_u32_e32 v23, vcc, 0, v57, vcc
	global_load_dwordx4 v[22:25], v[22:23], off nt
.LBB0_1010:
	s_or_b64 exec, exec, s[18:19]
	s_and_saveexec_b64 s[18:19], s[42:43]
	s_cbranch_execz .LBB0_1012
	v_lshl_add_u64 v[82:83], v[42:43], 0, v[58:59]
.LBB0_1012:
	s_or_b64 exec, exec, s[18:19]
	v_mov_b32_e32 v26, v1
	v_mov_b32_e32 v27, v1
	v_mov_b64_e32 v[28:29], v[26:27]
	s_and_saveexec_b64 s[18:19], s[44:45]
	s_cbranch_execz .LBB0_1014
	v_add_co_u32_e32 v26, vcc, 0x1000, v56
	s_nop 1
	v_addc_co_u32_e32 v27, vcc, 0, v57, vcc
	global_load_dwordx4 v[26:29], v[26:27], off offset:1024 nt
.LBB0_1014:
	s_or_b64 exec, exec, s[18:19]
	s_and_saveexec_b64 s[18:19], s[42:43]
	s_cbranch_execz .LBB0_1016
	v_lshl_add_u64 v[86:87], v[44:45], 0, v[58:59]
.LBB0_1016:
	s_or_b64 exec, exec, s[18:19]
	v_mov_b32_e32 v30, v1
	v_mov_b32_e32 v31, v1
	v_mov_b64_e32 v[32:33], v[30:31]
	s_and_saveexec_b64 s[18:19], s[44:45]
	s_cbranch_execz .LBB0_1018
	v_add_co_u32_e32 v30, vcc, 0x1000, v56
	s_nop 1
	v_addc_co_u32_e32 v31, vcc, 0, v57, vcc
	global_load_dwordx4 v[30:33], v[30:31], off offset:2048 nt
.LBB0_1018:
	s_or_b64 exec, exec, s[18:19]
	s_and_saveexec_b64 s[18:19], s[42:43]
	s_cbranch_execz .LBB0_1020
	v_lshl_add_u64 v[90:91], v[46:47], 0, v[58:59]
.LBB0_1020:
	s_or_b64 exec, exec, s[18:19]
	v_mov_b32_e32 v34, v1
	v_mov_b32_e32 v35, v1
	v_mov_b64_e32 v[36:37], v[34:35]
	s_and_saveexec_b64 s[18:19], s[44:45]
	s_cbranch_execz .LBB0_1022
	v_add_co_u32_e32 v34, vcc, 0x1000, v56
	s_nop 1
	v_addc_co_u32_e32 v35, vcc, 0, v57, vcc
	global_load_dwordx4 v[34:37], v[34:35], off offset:3072 nt
.LBB0_1022:
	s_or_b64 exec, exec, s[18:19]
	s_and_saveexec_b64 s[18:19], s[42:43]
	s_cbranch_execz .LBB0_1024
	v_lshl_add_u64 v[90:91], v[48:49], 0, v[58:59]
	s_waitcnt vmcnt(0)
	v_mov_b32_e32 v214, v6
	v_mov_b32_e32 v215, v7
	v_mov_b32_e32 v216, v8
	v_mov_b32_e32 v217, v9
	v_mov_b32_e32 v218, v10
	v_mov_b32_e32 v219, v11
	v_mov_b32_e32 v220, v12
	v_mov_b32_e32 v221, v13
	v_mov_b32_e32 v222, v14
	v_mov_b32_e32 v223, v15
	v_mov_b32_e32 v224, v16
	v_mov_b32_e32 v225, v17
	v_mov_b32_e32 v226, v18
	v_mov_b32_e32 v227, v19
	v_mov_b32_e32 v228, v20
	v_mov_b32_e32 v229, v21
	v_mov_b32_e32 v230, v22
	v_mov_b32_e32 v231, v23
	v_mov_b32_e32 v232, v24
	v_mov_b32_e32 v233, v25
	v_mov_b32_e32 v234, v26
	v_mov_b32_e32 v235, v27
	v_mov_b32_e32 v236, v28
	v_mov_b32_e32 v237, v29
	v_mov_b32_e32 v238, v30
	v_mov_b32_e32 v239, v31
	v_mov_b32_e32 v240, v32
	v_mov_b32_e32 v241, v33
	v_mov_b32_e32 v242, v34
	v_mov_b32_e32 v243, v35
	v_mov_b32_e32 v244, v36
	v_mov_b32_e32 v245, v37
	s_nop 3
	global_load_dwordx4 v[138:141], v174, s[98:99]
	global_load_dwordx4 v[142:145], v174, s[98:99] offset:1024
	global_load_dwordx4 v[146:149], v174, s[98:99] offset:2048
	global_load_dwordx4 v[150:153], v174, s[98:99] offset:3072
	s_add_u32 s98, s98, 0x200000
	s_addc_u32 s99, s99, 0
	global_load_dwordx4 v[154:157], v174, s[98:99]
	global_load_dwordx4 v[158:161], v174, s[98:99] offset:1024
	global_load_dwordx4 v[162:165], v174, s[98:99] offset:2048
	global_load_dwordx4 v[170:173], v174, s[98:99] offset:3072
	s_waitcnt vmcnt(4)
	v_pk_add_f32 v[214:215], v[214:215], v[138:139]
	v_pk_add_f32 v[216:217], v[216:217], v[140:141]
	v_pk_add_f32 v[218:219], v[218:219], v[142:143]
	v_pk_add_f32 v[220:221], v[220:221], v[144:145]
	v_pk_add_f32 v[222:223], v[222:223], v[146:147]
	v_pk_add_f32 v[224:225], v[224:225], v[148:149]
	v_pk_add_f32 v[226:227], v[226:227], v[150:151]
	v_pk_add_f32 v[228:229], v[228:229], v[152:153]
	s_add_u32 s98, s98, 0x200000
	s_addc_u32 s99, s99, 0
	global_load_dwordx4 v[138:141], v174, s[98:99]
	global_load_dwordx4 v[142:145], v174, s[98:99] offset:1024
	global_load_dwordx4 v[146:149], v174, s[98:99] offset:2048
	global_load_dwordx4 v[150:153], v174, s[98:99] offset:3072
	s_waitcnt vmcnt(4)
	v_pk_add_f32 v[214:215], v[214:215], v[154:155]
	v_pk_add_f32 v[216:217], v[216:217], v[156:157]
	v_pk_add_f32 v[218:219], v[218:219], v[158:159]
	v_pk_add_f32 v[220:221], v[220:221], v[160:161]
	v_pk_add_f32 v[222:223], v[222:223], v[162:163]
	v_pk_add_f32 v[224:225], v[224:225], v[164:165]
	v_pk_add_f32 v[226:227], v[226:227], v[170:171]
	v_pk_add_f32 v[228:229], v[228:229], v[172:173]
	s_add_u32 s98, s98, 0x200000
	s_addc_u32 s99, s99, 0
	global_load_dwordx4 v[154:157], v174, s[98:99]
	global_load_dwordx4 v[158:161], v174, s[98:99] offset:1024
	global_load_dwordx4 v[162:165], v174, s[98:99] offset:2048
	global_load_dwordx4 v[170:173], v174, s[98:99] offset:3072
	s_waitcnt vmcnt(4)
	v_pk_add_f32 v[214:215], v[214:215], v[138:139]
	v_pk_add_f32 v[216:217], v[216:217], v[140:141]
	v_pk_add_f32 v[218:219], v[218:219], v[142:143]
	v_pk_add_f32 v[220:221], v[220:221], v[144:145]
	v_pk_add_f32 v[222:223], v[222:223], v[146:147]
	v_pk_add_f32 v[224:225], v[224:225], v[148:149]
	v_pk_add_f32 v[226:227], v[226:227], v[150:151]
	v_pk_add_f32 v[228:229], v[228:229], v[152:153]
	s_add_u32 s98, s98, 0x200000
	s_addc_u32 s99, s99, 0
	global_load_dwordx4 v[138:141], v174, s[98:99]
	global_load_dwordx4 v[142:145], v174, s[98:99] offset:1024
	global_load_dwordx4 v[146:149], v174, s[98:99] offset:2048
	global_load_dwordx4 v[150:153], v174, s[98:99] offset:3072
	s_waitcnt vmcnt(4)
	v_pk_add_f32 v[214:215], v[214:215], v[154:155]
	v_pk_add_f32 v[216:217], v[216:217], v[156:157]
	v_pk_add_f32 v[218:219], v[218:219], v[158:159]
	v_pk_add_f32 v[220:221], v[220:221], v[160:161]
	v_pk_add_f32 v[222:223], v[222:223], v[162:163]
	v_pk_add_f32 v[224:225], v[224:225], v[164:165]
	v_pk_add_f32 v[226:227], v[226:227], v[170:171]
	v_pk_add_f32 v[228:229], v[228:229], v[172:173]
	s_add_u32 s98, s98, 0x200000
	s_addc_u32 s99, s99, 0
	global_load_dwordx4 v[154:157], v174, s[98:99]
	global_load_dwordx4 v[158:161], v174, s[98:99] offset:1024
	global_load_dwordx4 v[162:165], v174, s[98:99] offset:2048
	global_load_dwordx4 v[170:173], v174, s[98:99] offset:3072
	s_waitcnt vmcnt(4)
	v_pk_add_f32 v[214:215], v[214:215], v[138:139]
	v_pk_add_f32 v[216:217], v[216:217], v[140:141]
	v_pk_add_f32 v[218:219], v[218:219], v[142:143]
	v_pk_add_f32 v[220:221], v[220:221], v[144:145]
	v_pk_add_f32 v[222:223], v[222:223], v[146:147]
	v_pk_add_f32 v[224:225], v[224:225], v[148:149]
	v_pk_add_f32 v[226:227], v[226:227], v[150:151]
	v_pk_add_f32 v[228:229], v[228:229], v[152:153]
	s_add_u32 s98, s98, 0x200000
	s_addc_u32 s99, s99, 0
	global_load_dwordx4 v[138:141], v174, s[98:99]
	global_load_dwordx4 v[142:145], v174, s[98:99] offset:1024
	global_load_dwordx4 v[146:149], v174, s[98:99] offset:2048
	global_load_dwordx4 v[150:153], v174, s[98:99] offset:3072
	s_waitcnt vmcnt(4)
	v_pk_add_f32 v[214:215], v[214:215], v[154:155]
	v_pk_add_f32 v[216:217], v[216:217], v[156:157]
	v_pk_add_f32 v[218:219], v[218:219], v[158:159]
	v_pk_add_f32 v[220:221], v[220:221], v[160:161]
	v_pk_add_f32 v[222:223], v[222:223], v[162:163]
	v_pk_add_f32 v[224:225], v[224:225], v[164:165]
	v_pk_add_f32 v[226:227], v[226:227], v[170:171]
	v_pk_add_f32 v[228:229], v[228:229], v[172:173]
	s_add_u32 s98, s98, 0x200000
	s_addc_u32 s99, s99, 0
	global_load_dwordx4 v[154:157], v174, s[98:99]
	global_load_dwordx4 v[158:161], v174, s[98:99] offset:1024
	global_load_dwordx4 v[162:165], v174, s[98:99] offset:2048
	global_load_dwordx4 v[170:173], v174, s[98:99] offset:3072
	s_waitcnt vmcnt(4)
	v_pk_add_f32 v[214:215], v[214:215], v[138:139]
	v_pk_add_f32 v[216:217], v[216:217], v[140:141]
	v_pk_add_f32 v[218:219], v[218:219], v[142:143]
	v_pk_add_f32 v[220:221], v[220:221], v[144:145]
	v_pk_add_f32 v[222:223], v[222:223], v[146:147]
	v_pk_add_f32 v[224:225], v[224:225], v[148:149]
	v_pk_add_f32 v[226:227], v[226:227], v[150:151]
	v_pk_add_f32 v[228:229], v[228:229], v[152:153]
	s_waitcnt vmcnt(0)
	v_pk_add_f32 v[214:215], v[214:215], v[154:155]
	v_pk_add_f32 v[216:217], v[216:217], v[156:157]
	v_pk_add_f32 v[218:219], v[218:219], v[158:159]
	v_pk_add_f32 v[220:221], v[220:221], v[160:161]
	v_pk_add_f32 v[222:223], v[222:223], v[162:163]
	v_pk_add_f32 v[224:225], v[224:225], v[164:165]
	v_pk_add_f32 v[226:227], v[226:227], v[170:171]
	v_pk_add_f32 v[228:229], v[228:229], v[172:173]
	global_load_dwordx4 v[138:141], v174, s[100:101]
	global_load_dwordx4 v[142:145], v174, s[100:101] offset:1024
	global_load_dwordx4 v[146:149], v174, s[100:101] offset:2048
	global_load_dwordx4 v[150:153], v174, s[100:101] offset:3072
	s_add_u32 s100, s100, 0x200000
	s_addc_u32 s101, s101, 0
	global_load_dwordx4 v[154:157], v174, s[100:101]
	global_load_dwordx4 v[158:161], v174, s[100:101] offset:1024
	global_load_dwordx4 v[162:165], v174, s[100:101] offset:2048
	global_load_dwordx4 v[170:173], v174, s[100:101] offset:3072
	s_waitcnt vmcnt(4)
	v_pk_add_f32 v[230:231], v[230:231], v[138:139]
	v_pk_add_f32 v[232:233], v[232:233], v[140:141]
	v_pk_add_f32 v[234:235], v[234:235], v[142:143]
	v_pk_add_f32 v[236:237], v[236:237], v[144:145]
	v_pk_add_f32 v[238:239], v[238:239], v[146:147]
	v_pk_add_f32 v[240:241], v[240:241], v[148:149]
	v_pk_add_f32 v[242:243], v[242:243], v[150:151]
	v_pk_add_f32 v[244:245], v[244:245], v[152:153]
	s_add_u32 s100, s100, 0x200000
	s_addc_u32 s101, s101, 0
	global_load_dwordx4 v[138:141], v174, s[100:101]
	global_load_dwordx4 v[142:145], v174, s[100:101] offset:1024
	global_load_dwordx4 v[146:149], v174, s[100:101] offset:2048
	global_load_dwordx4 v[150:153], v174, s[100:101] offset:3072
	s_waitcnt vmcnt(4)
	v_pk_add_f32 v[230:231], v[230:231], v[154:155]
	v_pk_add_f32 v[232:233], v[232:233], v[156:157]
	v_pk_add_f32 v[234:235], v[234:235], v[158:159]
	v_pk_add_f32 v[236:237], v[236:237], v[160:161]
	v_pk_add_f32 v[238:239], v[238:239], v[162:163]
	v_pk_add_f32 v[240:241], v[240:241], v[164:165]
	v_pk_add_f32 v[242:243], v[242:243], v[170:171]
	v_pk_add_f32 v[244:245], v[244:245], v[172:173]
	s_add_u32 s100, s100, 0x200000
	s_addc_u32 s101, s101, 0
	global_load_dwordx4 v[154:157], v174, s[100:101]
	global_load_dwordx4 v[158:161], v174, s[100:101] offset:1024
	global_load_dwordx4 v[162:165], v174, s[100:101] offset:2048
	global_load_dwordx4 v[170:173], v174, s[100:101] offset:3072
	s_waitcnt vmcnt(4)
	v_pk_add_f32 v[230:231], v[230:231], v[138:139]
	v_pk_add_f32 v[232:233], v[232:233], v[140:141]
	v_pk_add_f32 v[234:235], v[234:235], v[142:143]
	v_pk_add_f32 v[236:237], v[236:237], v[144:145]
	v_pk_add_f32 v[238:239], v[238:239], v[146:147]
	v_pk_add_f32 v[240:241], v[240:241], v[148:149]
	v_pk_add_f32 v[242:243], v[242:243], v[150:151]
	v_pk_add_f32 v[244:245], v[244:245], v[152:153]
	s_add_u32 s100, s100, 0x200000
	s_addc_u32 s101, s101, 0
	global_load_dwordx4 v[138:141], v174, s[100:101]
	global_load_dwordx4 v[142:145], v174, s[100:101] offset:1024
	global_load_dwordx4 v[146:149], v174, s[100:101] offset:2048
	global_load_dwordx4 v[150:153], v174, s[100:101] offset:3072
	s_waitcnt vmcnt(4)
	v_pk_add_f32 v[230:231], v[230:231], v[154:155]
	v_pk_add_f32 v[232:233], v[232:233], v[156:157]
	v_pk_add_f32 v[234:235], v[234:235], v[158:159]
	v_pk_add_f32 v[236:237], v[236:237], v[160:161]
	v_pk_add_f32 v[238:239], v[238:239], v[162:163]
	v_pk_add_f32 v[240:241], v[240:241], v[164:165]
	v_pk_add_f32 v[242:243], v[242:243], v[170:171]
	v_pk_add_f32 v[244:245], v[244:245], v[172:173]
	s_add_u32 s100, s100, 0x200000
	s_addc_u32 s101, s101, 0
	global_load_dwordx4 v[154:157], v174, s[100:101]
	global_load_dwordx4 v[158:161], v174, s[100:101] offset:1024
	global_load_dwordx4 v[162:165], v174, s[100:101] offset:2048
	global_load_dwordx4 v[170:173], v174, s[100:101] offset:3072
	s_waitcnt vmcnt(4)
	v_pk_add_f32 v[230:231], v[230:231], v[138:139]
	v_pk_add_f32 v[232:233], v[232:233], v[140:141]
	v_pk_add_f32 v[234:235], v[234:235], v[142:143]
	v_pk_add_f32 v[236:237], v[236:237], v[144:145]
	v_pk_add_f32 v[238:239], v[238:239], v[146:147]
	v_pk_add_f32 v[240:241], v[240:241], v[148:149]
	v_pk_add_f32 v[242:243], v[242:243], v[150:151]
	v_pk_add_f32 v[244:245], v[244:245], v[152:153]
	s_add_u32 s100, s100, 0x200000
	s_addc_u32 s101, s101, 0
	global_load_dwordx4 v[138:141], v174, s[100:101]
	global_load_dwordx4 v[142:145], v174, s[100:101] offset:1024
	global_load_dwordx4 v[146:149], v174, s[100:101] offset:2048
	global_load_dwordx4 v[150:153], v174, s[100:101] offset:3072
	s_waitcnt vmcnt(4)
	v_pk_add_f32 v[230:231], v[230:231], v[154:155]
	v_pk_add_f32 v[232:233], v[232:233], v[156:157]
	v_pk_add_f32 v[234:235], v[234:235], v[158:159]
	v_pk_add_f32 v[236:237], v[236:237], v[160:161]
	v_pk_add_f32 v[238:239], v[238:239], v[162:163]
	v_pk_add_f32 v[240:241], v[240:241], v[164:165]
	v_pk_add_f32 v[242:243], v[242:243], v[170:171]
	v_pk_add_f32 v[244:245], v[244:245], v[172:173]
	s_add_u32 s100, s100, 0x200000
	s_addc_u32 s101, s101, 0
	global_load_dwordx4 v[154:157], v174, s[100:101]
	global_load_dwordx4 v[158:161], v174, s[100:101] offset:1024
	global_load_dwordx4 v[162:165], v174, s[100:101] offset:2048
	global_load_dwordx4 v[170:173], v174, s[100:101] offset:3072
	s_waitcnt vmcnt(4)
	v_pk_add_f32 v[230:231], v[230:231], v[138:139]
	v_pk_add_f32 v[232:233], v[232:233], v[140:141]
	v_pk_add_f32 v[234:235], v[234:235], v[142:143]
	v_pk_add_f32 v[236:237], v[236:237], v[144:145]
	v_pk_add_f32 v[238:239], v[238:239], v[146:147]
	v_pk_add_f32 v[240:241], v[240:241], v[148:149]
	v_pk_add_f32 v[242:243], v[242:243], v[150:151]
	v_pk_add_f32 v[244:245], v[244:245], v[152:153]
	s_waitcnt vmcnt(0)
	v_pk_add_f32 v[230:231], v[230:231], v[154:155]
	v_pk_add_f32 v[232:233], v[232:233], v[156:157]
	v_pk_add_f32 v[234:235], v[234:235], v[158:159]
	v_pk_add_f32 v[236:237], v[236:237], v[160:161]
	v_pk_add_f32 v[238:239], v[238:239], v[162:163]
	v_pk_add_f32 v[240:241], v[240:241], v[164:165]
	v_pk_add_f32 v[242:243], v[242:243], v[170:171]
	v_pk_add_f32 v[244:245], v[244:245], v[172:173]
	v_mov_b32_e32 v6, v214
	v_mov_b32_e32 v7, v215
	v_mov_b32_e32 v8, v216
	v_mov_b32_e32 v9, v217
	v_mov_b32_e32 v10, v218
	v_mov_b32_e32 v11, v219
	v_mov_b32_e32 v12, v220
	v_mov_b32_e32 v13, v221
	v_mov_b32_e32 v14, v222
	v_mov_b32_e32 v15, v223
	v_mov_b32_e32 v16, v224
	v_mov_b32_e32 v17, v225
	v_mov_b32_e32 v18, v226
	v_mov_b32_e32 v19, v227
	v_mov_b32_e32 v20, v228
	v_mov_b32_e32 v21, v229
	v_mov_b32_e32 v22, v230
	v_mov_b32_e32 v23, v231
	v_mov_b32_e32 v24, v232
	v_mov_b32_e32 v25, v233
	v_mov_b32_e32 v26, v234
	v_mov_b32_e32 v27, v235
	v_mov_b32_e32 v28, v236
	v_mov_b32_e32 v29, v237
	v_mov_b32_e32 v30, v238
	v_mov_b32_e32 v31, v239
	v_mov_b32_e32 v32, v240
	v_mov_b32_e32 v33, v241
	v_mov_b32_e32 v34, v242
	v_mov_b32_e32 v35, v243
	v_mov_b32_e32 v36, v244
	v_mov_b32_e32 v37, v245

	.amdhsa_kernel _Z16hymba_megakernel6Params
		.amdhsa_group_segment_fixed_size 0
		.amdhsa_private_segment_fixed_size 0
		.amdhsa_kernarg_size 464
		.amdhsa_user_sgpr_count 2
		.amdhsa_user_sgpr_dispatch_ptr 0
		.amdhsa_user_sgpr_queue_ptr 0
		.amdhsa_user_sgpr_kernarg_segment_ptr 1
		.amdhsa_user_sgpr_dispatch_id 0
		.amdhsa_user_sgpr_kernarg_preload_length 0
		.amdhsa_user_sgpr_kernarg_preload_offset 0
		.amdhsa_user_sgpr_private_segment_size 0
		.amdhsa_uses_dynamic_stack 0
		.amdhsa_enable_private_segment 0
		.amdhsa_system_sgpr_workgroup_id_x 1
		.amdhsa_system_sgpr_workgroup_id_y 0
		.amdhsa_system_sgpr_workgroup_id_z 0
		.amdhsa_system_sgpr_workgroup_info 0
		.amdhsa_system_vgpr_workitem_id 2
		.amdhsa_next_free_vgpr 256
		.amdhsa_next_free_sgpr 102
		.amdhsa_accum_offset 256
		.amdhsa_reserve_vcc 1
		.amdhsa_float_round_mode_32 0
		.amdhsa_float_round_mode_16_64 0
		.amdhsa_float_denorm_mode_32 3
		.amdhsa_float_denorm_mode_16_64 3
		.amdhsa_dx10_clamp 1
		.amdhsa_ieee_mode 1
		.amdhsa_fp16_overflow 0
		.amdhsa_tg_split 0
		.amdhsa_exception_fp_ieee_invalid_op 0
		.amdhsa_exception_fp_denorm_src 0
		.amdhsa_exception_fp_ieee_div_zero 0
		.amdhsa_exception_fp_ieee_overflow 0
		.amdhsa_exception_fp_ieee_underflow 0
		.amdhsa_exception_fp_ieee_inexact 0
		.amdhsa_exception_int_div_zero 0
	.end_amdhsa_kernel

amdhsa.kernels:
  - .agpr_count:     0
    .args:
      - .offset:         0
        .size:           208
        .value_kind:     by_value
      - .offset:         208
        .size:           4
        .value_kind:     hidden_block_count_x
      - .offset:         212
        .size:           4
        .value_kind:     hidden_block_count_y
      - .offset:         216
        .size:           4
        .value_kind:     hidden_block_count_z
      - .offset:         220
        .size:           2
        .value_kind:     hidden_group_size_x
      - .offset:         222
        .size:           2
        .value_kind:     hidden_group_size_y
      - .offset:         224
        .size:           2
        .value_kind:     hidden_group_size_z
      - .offset:         226
        .size:           2
        .value_kind:     hidden_remainder_x
      - .offset:         228
        .size:           2
        .value_kind:     hidden_remainder_y
      - .offset:         230
        .size:           2
        .value_kind:     hidden_remainder_z
      - .offset:         248
        .size:           8
        .value_kind:     hidden_global_offset_x
      - .offset:         256
        .size:           8
        .value_kind:     hidden_global_offset_y
      - .offset:         264
        .size:           8
        .value_kind:     hidden_global_offset_z
      - .offset:         272
        .size:           2
        .value_kind:     hidden_grid_dims
      - .offset:         296
        .size:           8
        .value_kind:     hidden_multigrid_sync_arg
      - .offset:         328
        .size:           4
        .value_kind:     hidden_dynamic_lds_size
    .group_segment_fixed_size: 0
    .kernarg_segment_align: 8
    .kernarg_segment_size: 464
    .language:       OpenCL C
    .language_version:
      - 2
      - 0
    .max_flat_workgroup_size: 512
    .name:           _Z16hymba_megakernel6Params
    .private_segment_fixed_size: 0
    .sgpr_count:     108
    .sgpr_spill_count: 136
    .symbol:         _Z16hymba_megakernel6Params.kd
    .uniform_work_group_size: 1
    .uses_dynamic_stack: false
    .vgpr_count:     256
    .vgpr_spill_count: 0
    .wavefront_size: 64
